# v46 + layer-B q-norm gain loads hoisted out of the attention unit loop, removing the vmcnt(1)/vmcnt(0) that drained the next-unit prefetch every unit
# baseline (speedup 1.0000x reference)
.Lmy_prio_b:
	v_readlane_b32 s26, v252, 26
	s_nop 1
	v_mov_b32_e32 v186, s26
	ds_read_b64 v[186:187], v186
	v_lshlrev_b32_e32 v188, 3, v184
	v_ashrrev_i32_e32 v189, 31, v188
	s_waitcnt lgkmcnt(0)
	v_lshl_add_u64 v[234:235], v[188:189], 2, v[186:187]
	global_load_dwordx4 v[186:189], v[234:235], off
	global_load_dwordx4 v[190:193], v[234:235], off offset:16
	global_load_dwordx4 v[194:197], v[234:235], off offset:80
	global_load_dwordx4 v[198:201], v[234:235], off offset:64
	global_load_dwordx4 v[202:205], v[234:235], off offset:144
	global_load_dwordx4 v[206:209], v[234:235], off offset:128
	global_load_dwordx4 v[226:229], v[234:235], off offset:208
	global_load_dwordx4 v[230:233], v[234:235], off offset:192
	s_waitcnt vmcnt(0)
	s_branch .LBB0_583

.LBB0_587:
	s_or_b64 exec, exec, s[10:11]
	v_and_b32_e32 v2, 64, v213
	v_readlane_b32 s10, v252, 26
	v_mov_b32_e32 v154, v184
	v_add_u32_e32 v5, 64, v2
	v_mov_b32_e32 v2, s10
	v_xor_b32_e32 v4, 32, v213
	ds_read_b64 v[2:3], v2
	v_cmp_lt_i32_e32 vcc, v4, v5
	s_waitcnt vmcnt(0)
	v_lshlrev_b32_e32 v166, 16, v74
	v_and_b32_e32 v167, 0xffff0000, v74
	v_cndmask_b32_e32 v4, v213, v4, vcc
	v_lshlrev_b32_e32 v153, 2, v4
	v_lshlrev_b32_e32 v4, 3, v154
	v_ashrrev_i32_e32 v5, 31, v4
	s_waitcnt lgkmcnt(0)
	v_lshl_add_u64 v[6:7], v[4:5], 2, v[2:3]
	v_mov_b64_e32 v[92:93], v[186:187]
	v_mov_b64_e32 v[94:95], v[188:189]
	v_mov_b64_e32 v[100:101], v[190:191]
	v_mov_b64_e32 v[102:103], v[192:193]
	v_mov_b64_e32 v[18:19], v[194:195]
	v_mov_b64_e32 v[20:21], v[196:197]
	v_mov_b64_e32 v[22:23], v[198:199]
	v_mov_b64_e32 v[24:25], v[200:201]
	v_mov_b64_e32 v[10:11], v[202:203]
	v_mov_b64_e32 v[12:13], v[204:205]
	v_mov_b64_e32 v[14:15], v[206:207]
	v_mov_b64_e32 v[16:17], v[208:209]
	v_mov_b64_e32 v[2:3], v[226:227]
	v_mov_b64_e32 v[4:5], v[228:229]
	v_mov_b64_e32 v[6:7], v[230:231]
	v_mov_b64_e32 v[8:9], v[232:233]
	v_lshlrev_b32_e32 v162, 16, v75
	v_and_b32_e32 v163, 0xffff0000, v75
	v_pk_mul_f32 v[168:169], v[166:167], v[166:167]
	v_pk_mul_f32 v[164:165], v[162:163], v[162:163]
	v_add_f32_e32 v125, v168, v169
	v_lshlrev_b32_e32 v158, 16, v76
	v_and_b32_e32 v159, 0xffff0000, v76
	v_add_f32_e32 v125, v164, v125
	v_pk_mul_f32 v[160:161], v[158:159], v[158:159]
	v_add_f32_e32 v125, v165, v125
	v_lshlrev_b32_e32 v142, 16, v77
	v_and_b32_e32 v143, 0xffff0000, v77
	v_add_f32_e32 v125, v160, v125
	v_pk_mul_f32 v[156:157], v[142:143], v[142:143]
	v_add_f32_e32 v125, v161, v125
	s_waitcnt vmcnt(10)
	v_lshlrev_b32_e32 v48, 16, v78
	v_and_b32_e32 v49, 0xffff0000, v78
	v_add_f32_e32 v125, v156, v125
	v_pk_mul_f32 v[140:141], v[48:49], v[48:49]
	v_add_f32_e32 v125, v157, v125
	v_lshlrev_b32_e32 v46, 16, v79
	v_and_b32_e32 v47, 0xffff0000, v79
	v_add_f32_e32 v125, v140, v125
	v_pk_mul_f32 v[138:139], v[46:47], v[46:47]
	v_add_f32_e32 v125, v141, v125
	v_lshlrev_b32_e32 v44, 16, v80
	v_and_b32_e32 v45, 0xffff0000, v80
	v_add_f32_e32 v125, v138, v125
	v_pk_mul_f32 v[136:137], v[44:45], v[44:45]
	v_add_f32_e32 v125, v139, v125
	v_lshlrev_b32_e32 v42, 16, v81
	v_and_b32_e32 v43, 0xffff0000, v81
	v_add_f32_e32 v125, v136, v125
	v_pk_mul_f32 v[134:135], v[42:43], v[42:43]
	v_add_f32_e32 v125, v137, v125
	s_waitcnt vmcnt(9)
	v_lshlrev_b32_e32 v40, 16, v82
	v_and_b32_e32 v41, 0xffff0000, v82
	v_add_f32_e32 v125, v134, v125
	v_pk_mul_f32 v[132:133], v[40:41], v[40:41]
	v_add_f32_e32 v125, v135, v125
	v_lshlrev_b32_e32 v38, 16, v83
	v_and_b32_e32 v39, 0xffff0000, v83
	v_add_f32_e32 v125, v132, v125
	v_pk_mul_f32 v[130:131], v[38:39], v[38:39]
	v_add_f32_e32 v125, v133, v125
	v_lshlrev_b32_e32 v36, 16, v84
	v_and_b32_e32 v37, 0xffff0000, v84
	v_add_f32_e32 v125, v130, v125
	v_pk_mul_f32 v[128:129], v[36:37], v[36:37]
	v_add_f32_e32 v125, v131, v125
	v_lshlrev_b32_e32 v34, 16, v85
	v_and_b32_e32 v35, 0xffff0000, v85
	v_add_f32_e32 v125, v128, v125
	v_pk_mul_f32 v[126:127], v[34:35], v[34:35]
	v_add_f32_e32 v125, v129, v125
	s_waitcnt vmcnt(8)
	v_lshlrev_b32_e32 v32, 16, v86
	v_and_b32_e32 v33, 0xffff0000, v86
	v_add_f32_e32 v125, v126, v125
	v_pk_mul_f32 v[104:105], v[32:33], v[32:33]
	v_add_f32_e32 v125, v127, v125
	v_lshlrev_b32_e32 v30, 16, v87
	v_and_b32_e32 v31, 0xffff0000, v87
	v_add_f32_e32 v104, v104, v125
	v_pk_mul_f32 v[98:99], v[30:31], v[30:31]
	v_add_f32_e32 v104, v105, v104
	v_lshlrev_b32_e32 v28, 16, v88
	v_and_b32_e32 v29, 0xffff0000, v88
	v_add_f32_e32 v98, v98, v104
	v_pk_mul_f32 v[96:97], v[28:29], v[28:29]
	v_add_f32_e32 v98, v99, v98
	v_lshlrev_b32_e32 v26, 16, v89
	v_and_b32_e32 v27, 0xffff0000, v89
	v_add_f32_e32 v96, v96, v98
	v_pk_mul_f32 v[90:91], v[26:27], v[26:27]
	v_add_f32_e32 v96, v97, v96
	v_add_f32_e32 v90, v90, v96
	v_add_f32_e32 v90, v91, v90
	ds_bpermute_b32 v91, v153, v90
	s_add_i32 s22, s23, s73
	s_cmpk_gt_i32 s22, 0x81f
	s_waitcnt lgkmcnt(0)
	s_barrier
	v_add_f32_e32 v90, v90, v91
	v_fmamk_f32 v90, v90, 0x3c800000, v214
	v_rsq_f32_e32 v104, v90
	s_waitcnt vmcnt(7)
	v_pk_mul_f32 v[90:91], v[92:93], v[104:105] op_sel_hi:[1,0]
	s_nop 0
	v_pk_mul_f32 v[98:99], v[90:91], v[166:167]
	s_waitcnt vmcnt(6)
	v_pk_mul_f32 v[90:91], v[100:101], v[104:105] op_sel_hi:[1,0]
	ds_bpermute_b32 v126, v153, v98
	v_pk_mul_f32 v[92:93], v[90:91], v[158:159]
	v_pk_mul_f32 v[90:91], v[94:95], v[104:105] op_sel_hi:[1,0]
	ds_bpermute_b32 v127, v153, v99
	v_pk_mul_f32 v[96:97], v[90:91], v[162:163]
	v_pk_mul_f32 v[90:91], v[102:103], v[104:105] op_sel_hi:[1,0]
	ds_bpermute_b32 v102, v153, v96
	v_pk_mul_f32 v[90:91], v[90:91], v[142:143]
	ds_bpermute_b32 v103, v153, v97
	ds_bpermute_b32 v100, v153, v92
	ds_bpermute_b32 v101, v153, v93
	ds_bpermute_b32 v94, v153, v90
	ds_bpermute_b32 v95, v153, v91
	s_cbranch_scc1 .LBB0_595
	s_ashr_i32 s10, s22, 5
	s_bfe_u32 s11, s22, 0x30002
	s_max_i32 s12, s10, 4
	s_mul_i32 s10, s11, 0x810
	s_lshl_b32 s11, s12, 5
	s_add_i32 s52, s11, 0xffffff80
	s_add_i32 s12, s52, s10
	s_mov_b32 s13, s53
	s_and_b32 s24, s22, 3
	s_lshl_b64 s[12:13], s[12:13], 9
	s_add_u32 s11, s3, s12
	s_addc_u32 s12, s16, s13
	s_lshl_b32 s13, s24, 7
	s_add_u32 s14, s11, s13
	s_addc_u32 s15, s12, 0
	s_lshl_b32 s11, s22, 6
	s_and_b32 s11, s11, 0x7c0
	s_mulk_i32 s11, 0x1080
	s_add_u32 s11, s17, s11
	s_addc_u32 s25, s18, 0
	s_lshl_b64 s[12:13], s[52:53], 1
	s_add_u32 s12, s11, s12
	s_addc_u32 s13, s25, s13
	v_lshl_add_u64 v[74:75], s[14:15], 0, v[0:1]
	s_and_saveexec_b64 s[14:15], s[4:5]
	s_cbranch_execz .LBB0_590
	v_lshl_add_u64 v[50:51], s[12:13], 0, v[108:109]
	v_lshl_add_u64 v[54:55], v[110:111], 1, v[50:51]
	v_lshl_add_u64 v[50:51], v[74:75], 0, v[106:107]
	global_load_dwordx4 v[50:53], v[50:51], off
	s_nop 0
	global_load_dwordx4 v[54:57], v[54:55], off

.LBB0_595:
	s_and_b32 s12, s23, 0xffffffe0
	v_or_b32_e32 v105, s12, v177
	v_min_i32_e32 v125, 0x80f, v105
	v_cvt_f32_i32_e32 v105, v125
	s_mov_b32 s10, 0x6dc9c883
	s_mov_b32 s11, 0x3fc45f30
	v_cvt_f64_f32_e32 v[128:129], v105
	v_mul_f32_e32 v132, 0x3e4693af, v105
	v_mul_f64 v[130:131], v[128:129], s[10:11]
	v_cvt_f64_f32_e32 v[134:135], v132
	v_rndne_f64_e32 v[130:131], v[130:131]
	v_fma_f64 v[128:129], v[128:129], s[10:11], -v[130:131]
	v_mul_f64 v[130:131], v[134:135], s[10:11]
	v_rndne_f64_e32 v[130:131], v[130:131]
	v_fma_f64 v[130:131], v[134:135], s[10:11], -v[130:131]
	v_cvt_f32_f64_e32 v129, v[128:129]
	v_cvt_f32_f64_e32 v130, v[130:131]
	v_cos_f32_e32 v128, v129
	v_sin_f32_e32 v132, v129
	v_cos_f32_e32 v129, v130
	v_sin_f32_e32 v133, v130
	v_mul_f32_e32 v130, 0x3d1a08c8, v105
	v_cvt_f64_f32_e32 v[130:131], v130
	v_mul_f64 v[134:135], v[130:131], s[10:11]
	v_rndne_f64_e32 v[134:135], v[134:135]
	v_fma_f64 v[130:131], v[130:131], s[10:11], -v[134:135]
	v_cvt_f32_f64_e32 v131, v[130:131]
	v_cos_f32_e32 v130, v131
	v_sin_f32_e32 v134, v131
	v_mul_f32_e32 v131, 0x3beef74e, v105
	v_cvt_f64_f32_e32 v[136:137], v131
	v_mul_f64 v[138:139], v[136:137], s[10:11]
	v_rndne_f64_e32 v[138:139], v[138:139]
	v_fma_f64 v[136:137], v[136:137], s[10:11], -v[138:139]
	v_cvt_f32_f64_e32 v135, v[136:137]
	v_mul_f32_e32 v136, 0x3ab95d22, v105
	v_cvt_f64_f32_e32 v[136:137], v136
	v_mul_f64 v[138:139], v[136:137], s[10:11]
	v_rndne_f64_e32 v[138:139], v[138:139]
	v_fma_f64 v[136:137], v[136:137], s[10:11], -v[138:139]
	v_cvt_f32_f64_e32 v137, v[136:137]
	v_cos_f32_e32 v136, v137
	v_sin_f32_e32 v138, v137
	v_mul_f32_e32 v137, 0x398fc8f8, v105
	v_cvt_f64_f32_e32 v[140:141], v137
	v_mul_f64 v[142:143], v[140:141], s[10:11]
	v_rndne_f64_e32 v[142:143], v[142:143]
	v_fma_f64 v[140:141], v[140:141], s[10:11], -v[142:143]
	v_cvt_f32_f64_e32 v139, v[140:141]
	v_mul_f32_e32 v140, 0x385f10c5, v105
	v_mul_f32_e32 v105, 0x372d07a8, v105
	v_cvt_f64_f32_e32 v[140:141], v140
	v_cvt_f64_f32_e32 v[156:157], v105
	v_mul_f64 v[142:143], v[140:141], s[10:11]
	v_mul_f64 v[158:159], v[156:157], s[10:11]
	v_rndne_f64_e32 v[142:143], v[142:143]
	v_rndne_f64_e32 v[158:159], v[158:159]
	v_fma_f64 v[140:141], v[140:141], s[10:11], -v[142:143]
	v_fma_f64 v[156:157], v[156:157], s[10:11], -v[158:159]
	v_cvt_f32_f64_e32 v141, v[140:141]
	v_cvt_f32_f64_e32 v105, v[156:157]
	v_cos_f32_e32 v131, v135
	v_sin_f32_e32 v135, v135
	v_cos_f32_e32 v137, v139
	v_sin_f32_e32 v139, v139
	v_cos_f32_e32 v140, v141
	v_sin_f32_e32 v142, v141
	v_cos_f32_e32 v141, v105
	v_sin_f32_e32 v143, v105
	s_ashr_i32 s10, s23, 5
	s_max_i32 s11, s10, 4
	s_add_i32 s13, s11, -4
	s_cmp_lt_i32 s10, s13
	s_cbranch_scc1 .LBB0_602
	v_mov_b32_e32 v105, v104
	v_pk_mul_f32 v[4:5], v[104:105], v[4:5]
	v_cmp_eq_u32_e32 vcc, 0, v154
	v_pk_mul_f32 v[2:3], v[104:105], v[2:3]
	v_pk_mul_f32 v[4:5], v[4:5], v[26:27]
	s_waitcnt lgkmcnt(6)
	v_pk_mul_f32 v[26:27], v[132:133], v[126:127]
	v_pk_mul_f32 v[6:7], v[104:105], v[6:7]
	v_pk_mul_f32 v[2:3], v[2:3], v[28:29]
	v_pk_mul_f32 v[8:9], v[104:105], v[8:9]
	v_cndmask_b32_e64 v27, v27, -v27, vcc
	v_cndmask_b32_e64 v26, v26, -v26, vcc
	s_waitcnt lgkmcnt(4)
	v_pk_mul_f32 v[28:29], v[134:135], v[102:103]
	v_pk_mul_f32 v[6:7], v[6:7], v[32:33]
	v_pk_mul_f32 v[8:9], v[8:9], v[30:31]
	v_pk_fma_f32 v[26:27], v[128:129], v[98:99], v[26:27]
	v_cndmask_b32_e64 v29, v29, -v29, vcc
	v_cndmask_b32_e64 v28, v28, -v28, vcc
	s_waitcnt lgkmcnt(2)
	v_pk_mul_f32 v[30:31], v[138:139], v[100:101]
	s_waitcnt lgkmcnt(0)
	v_pk_mul_f32 v[32:33], v[142:143], v[94:95]
	s_mov_b32 s14, 0x3e38aa3b
	v_pk_mul_f32 v[22:23], v[22:23], v[104:105]
	v_pk_mul_f32 v[18:19], v[104:105], v[18:19]
	v_pk_mul_f32 v[14:15], v[104:105], v[14:15]
	v_pk_mul_f32 v[10:11], v[104:105], v[10:11]
	v_pk_fma_f32 v[28:29], v[130:131], v[96:97], v[28:29]
	v_cndmask_b32_e64 v31, v31, -v31, vcc
	v_cndmask_b32_e64 v30, v30, -v30, vcc
	v_cndmask_b32_e64 v33, v33, -v33, vcc
	v_cndmask_b32_e64 v32, v32, -v32, vcc
	v_pk_mul_f32 v[26:27], v[26:27], s[14:15] op_sel_hi:[1,0]
	v_pk_mul_f32 v[22:23], v[22:23], v[48:49]
	v_pk_mul_f32 v[18:19], v[18:19], v[44:45]
	v_pk_mul_f32 v[24:25], v[24:25], v[104:105]
	v_pk_mul_f32 v[20:21], v[104:105], v[20:21]
	v_pk_mul_f32 v[14:15], v[14:15], v[40:41]
	v_pk_mul_f32 v[10:11], v[10:11], v[36:37]
	v_pk_mul_f32 v[16:17], v[104:105], v[16:17]
	v_pk_mul_f32 v[12:13], v[104:105], v[12:13]
	v_pk_fma_f32 v[30:31], v[136:137], v[92:93], v[30:31]
	v_pk_fma_f32 v[32:33], v[140:141], v[90:91], v[32:33]
	v_cvt_pk_bf16_f32 v90, v26, v27
	v_pk_mul_f32 v[26:27], v[28:29], s[14:15] op_sel_hi:[1,0]
	v_pk_mul_f32 v[2:3], v[2:3], s[14:15] op_sel_hi:[1,0]
	v_pk_mul_f32 v[24:25], v[24:25], v[46:47]
	v_pk_mul_f32 v[20:21], v[20:21], v[42:43]
	v_pk_mul_f32 v[16:17], v[16:17], v[38:39]
	v_pk_mul_f32 v[12:13], v[12:13], v[34:35]
	v_cvt_pk_bf16_f32 v91, v26, v27
	v_pk_mul_f32 v[26:27], v[30:31], s[14:15] op_sel_hi:[1,0]
	v_pk_mul_f32 v[22:23], v[22:23], s[14:15] op_sel_hi:[1,0]
	v_pk_mul_f32 v[18:19], v[18:19], s[14:15] op_sel_hi:[1,0]
	v_pk_mul_f32 v[14:15], v[14:15], s[14:15] op_sel_hi:[1,0]
	v_pk_mul_f32 v[10:11], v[10:11], s[14:15] op_sel_hi:[1,0]
	v_pk_mul_f32 v[6:7], v[6:7], s[14:15] op_sel_hi:[1,0]
	v_cvt_pk_bf16_f32 v104, v2, v3
	v_pk_mul_f32 v[2:3], v[4:5], s[14:15] op_sel_hi:[1,0]
	s_sub_i32 s10, s10, s11
	s_lshl_b32 s11, s11, 5
	v_cvt_pk_bf16_f32 v92, v26, v27
	v_pk_mul_f32 v[26:27], v[32:33], s[14:15] op_sel_hi:[1,0]
	v_cvt_pk_bf16_f32 v94, v22, v23
	v_pk_mul_f32 v[22:23], v[24:25], s[14:15] op_sel_hi:[1,0]
	v_cvt_pk_bf16_f32 v96, v18, v19
	v_pk_mul_f32 v[18:19], v[20:21], s[14:15] op_sel_hi:[1,0]
	v_cvt_pk_bf16_f32 v98, v14, v15
	v_pk_mul_f32 v[14:15], v[16:17], s[14:15] op_sel_hi:[1,0]
	v_cvt_pk_bf16_f32 v100, v10, v11
	v_pk_mul_f32 v[10:11], v[12:13], s[14:15] op_sel_hi:[1,0]
	v_cvt_pk_bf16_f32 v102, v6, v7
	v_pk_mul_f32 v[6:7], v[8:9], s[14:15] op_sel_hi:[1,0]
	v_cvt_pk_bf16_f32 v105, v2, v3
	v_subrev_u32_e32 v2, s11, v125
	v_cvt_pk_bf16_f32 v93, v26, v27
	v_cvt_pk_bf16_f32 v95, v22, v23
	v_cvt_pk_bf16_f32 v97, v18, v19
	v_cvt_pk_bf16_f32 v99, v14, v15
	v_cvt_pk_bf16_f32 v101, v10, v11
	v_cvt_pk_bf16_f32 v103, v6, v7
	s_add_i32 s10, s10, 5
	v_add_u32_e32 v127, 0x80, v2
	v_mov_b32_e32 v18, v1
	v_mov_b32_e32 v19, v1
	v_mov_b32_e32 v20, v1
	v_mov_b32_e32 v21, v1
	v_mov_b32_e32 v22, v1
	v_mov_b32_e32 v23, v1
	v_mov_b32_e32 v24, v1
	v_mov_b32_e32 v25, v1
	v_mov_b32_e32 v26, v1
	v_mov_b32_e32 v27, v1
	v_mov_b32_e32 v28, v1
	v_mov_b32_e32 v29, v1
	v_mov_b32_e32 v30, v1
	v_mov_b32_e32 v31, v1
	v_mov_b32_e32 v32, v1
	v_mov_b32_e32 v33, v1
	v_mov_b32_e32 v2, v1
	v_mov_b32_e32 v3, v1
	v_mov_b32_e32 v4, v1
	v_mov_b32_e32 v5, v1
	v_mov_b32_e32 v6, v1
	v_mov_b32_e32 v7, v1
	v_mov_b32_e32 v8, v1
	v_mov_b32_e32 v9, v1
	v_mov_b32_e32 v10, v1
	v_mov_b32_e32 v11, v1
	v_mov_b32_e32 v12, v1
	v_mov_b32_e32 v13, v1
	v_mov_b32_e32 v14, v1
	v_mov_b32_e32 v15, v1
	v_mov_b32_e32 v16, v1
	v_mov_b32_e32 v17, v1
	v_mov_b32_e32 v126, 0xff800000
	v_mov_b32_e32 v125, 0
	v_mov_b32_e32 v128, v144
	v_mov_b32_e32 v129, v146
	s_branch .LBB0_598
